# phase-0 mod GEMV preamble: the conditioning-vector loads issued together and waited on once instead of 17 serial load/wait rounds
# baseline (speedup 1.0000x reference)
; __device__ __forceinline__ const float* inp(int k) { const CAS cfptr* p = (const CAS cfptr*)__builtin_amdgcn_kernarg_segment_ptr(); asm volatile("" : "+s"(p)); return p[k]; }
; __device__ __forceinline__ void p0a(Frame& F, const Args& A) {
;     ...
;     for (int unit = F.gw; unit < 2 * 96 * 8; unit += F.NGW) {
;         const int l = unit / 768, r2 = unit % 768, cb = r2 >> 3, ks = r2 & 7, k0 = ks * 128, n = cb * 64 + f_lane;
; #pragma unroll
;         for (int r = 0; r < 9; ++r)
; #pragma unroll
;             for (int h = 0; h < 2; ++h) { const int k = k0 + h * 64 + f_lane; const float v = (r < 8) ? inp(1)[r * DM + k] : inp(3)[k]; scr[r * 128 + h * 64 + f_lane] = v * __builtin_amdgcn_rcpf(1.0f + __expf(-v)); }
.LBB0_123:
	s_mul_hi_i32 s8, s23, 0x2aaaaaab
	s_lshr_b32 s9, s8, 31
	s_ashr_i32 s24, s8, 7
	s_add_i32 s24, s24, s9
	s_mov_b64 s[8:9], s[0:1]
	s_load_dwordx2 s[26:27], s[8:9], 0x8
	s_mul_i32 s8, s24, 0x300
	s_sub_i32 s9, s23, s8
	s_and_b32 s8, s9, 7
	v_lshl_or_b32 v0, s8, 9, v15
	s_waitcnt lgkmcnt(0)
	global_load_dword v120, v0, s[26:27]
	s_mov_b64 s[26:27], s[0:1]
	s_lshl_b32 s9, s9, 3
	s_andn2_b32 s9, s9, 63
	s_cmp_lg_u32 s8, 0
	v_mov_b32_e32 v6, 0
	s_load_dwordx2 s[26:27], s[26:27], 0x8
	s_waitcnt lgkmcnt(0)
	global_load_dword v122, v0, s[26:27] offset:256
	s_mov_b64 s[26:27], s[0:1]
	s_load_dwordx2 s[26:27], s[26:27], 0x8
	s_waitcnt lgkmcnt(0)
	v_lshl_add_u64 v[124:125], s[26:27], 0, v[0:1]
	v_add_co_u32_e32 v124, vcc, s10, v124
	s_mov_b64 s[26:27], s[0:1]
	s_nop 0
	v_addc_co_u32_e32 v125, vcc, 0, v125, vcc
	global_load_dword v124, v[124:125], off
	s_load_dwordx2 s[26:27], s[26:27], 0x8
	s_waitcnt lgkmcnt(0)
	v_lshl_add_u64 v[126:127], s[26:27], 0, v[0:1]
	v_add_co_u32_e32 v126, vcc, s10, v126
	s_mov_b64 s[26:27], s[0:1]
	s_nop 0
	v_addc_co_u32_e32 v127, vcc, 0, v127, vcc
	global_load_dword v126, v[126:127], off offset:256
	s_load_dwordx2 s[26:27], s[26:27], 0x8
	s_waitcnt lgkmcnt(0)
	v_lshl_add_u64 v[128:129], s[26:27], 0, v[0:1]
	v_add_co_u32_e32 v128, vcc, s11, v128
	s_mov_b64 s[26:27], s[0:1]
	s_nop 0
	v_addc_co_u32_e32 v129, vcc, 0, v129, vcc
	global_load_dword v128, v[128:129], off
	s_load_dwordx2 s[26:27], s[26:27], 0x8
	s_waitcnt lgkmcnt(0)
	v_lshl_add_u64 v[130:131], s[26:27], 0, v[0:1]
	v_add_co_u32_e32 v130, vcc, s11, v130
	s_mov_b64 s[26:27], s[0:1]
	s_nop 0
	v_addc_co_u32_e32 v131, vcc, 0, v131, vcc
	global_load_dword v130, v[130:131], off offset:256
	s_load_dwordx2 s[26:27], s[26:27], 0x8
	s_waitcnt lgkmcnt(0)
	v_lshl_add_u64 v[132:133], s[26:27], 0, v[0:1]
	v_add_co_u32_e32 v132, vcc, s12, v132
	s_mov_b64 s[26:27], s[0:1]
	s_nop 0
	v_addc_co_u32_e32 v133, vcc, 0, v133, vcc
	global_load_dword v132, v[132:133], off
	s_load_dwordx2 s[26:27], s[26:27], 0x8
	s_waitcnt lgkmcnt(0)
	v_lshl_add_u64 v[134:135], s[26:27], 0, v[0:1]
	v_add_co_u32_e32 v134, vcc, s12, v134
	s_mov_b64 s[26:27], s[0:1]
	s_nop 0
	v_addc_co_u32_e32 v135, vcc, 0, v135, vcc
	global_load_dword v134, v[134:135], off offset:256
	s_load_dwordx2 s[26:27], s[26:27], 0x8
	s_waitcnt lgkmcnt(0)
	v_lshl_add_u64 v[136:137], s[26:27], 0, v[0:1]
	v_add_co_u32_e32 v136, vcc, s13, v136
	s_mov_b64 s[26:27], s[0:1]
	s_nop 0
	v_addc_co_u32_e32 v137, vcc, 0, v137, vcc
	global_load_dword v136, v[136:137], off
	s_load_dwordx2 s[26:27], s[26:27], 0x8
	s_waitcnt lgkmcnt(0)
	v_lshl_add_u64 v[138:139], s[26:27], 0, v[0:1]
	v_add_co_u32_e32 v138, vcc, s13, v138
	s_mov_b64 s[26:27], s[0:1]
	s_nop 0
	v_addc_co_u32_e32 v139, vcc, 0, v139, vcc
	global_load_dword v138, v[138:139], off offset:256
	s_load_dwordx2 s[26:27], s[26:27], 0x8
	s_waitcnt lgkmcnt(0)
	v_lshl_add_u64 v[140:141], s[26:27], 0, v[0:1]
	v_add_co_u32_e32 v140, vcc, s14, v140
	s_mov_b64 s[26:27], s[0:1]
	s_nop 0
	v_addc_co_u32_e32 v141, vcc, 0, v141, vcc
	global_load_dword v140, v[140:141], off
	s_load_dwordx2 s[26:27], s[26:27], 0x8
	s_waitcnt lgkmcnt(0)
	v_lshl_add_u64 v[142:143], s[26:27], 0, v[0:1]
	v_add_co_u32_e32 v142, vcc, s14, v142
	s_mov_b64 s[26:27], s[0:1]
	s_nop 0
	v_addc_co_u32_e32 v143, vcc, 0, v143, vcc
	global_load_dword v142, v[142:143], off offset:256
	s_load_dwordx2 s[26:27], s[26:27], 0x8
	s_waitcnt lgkmcnt(0)
	v_lshl_add_u64 v[144:145], s[26:27], 0, v[0:1]
	v_add_co_u32_e32 v144, vcc, s15, v144
	s_mov_b64 s[26:27], s[0:1]
	s_nop 0
	v_addc_co_u32_e32 v145, vcc, 0, v145, vcc
	global_load_dword v144, v[144:145], off
	s_load_dwordx2 s[26:27], s[26:27], 0x8
	s_waitcnt lgkmcnt(0)
	v_lshl_add_u64 v[146:147], s[26:27], 0, v[0:1]
	v_add_co_u32_e32 v146, vcc, s15, v146
	s_mov_b64 s[26:27], s[0:1]
	s_nop 0
	v_addc_co_u32_e32 v147, vcc, 0, v147, vcc
	global_load_dword v146, v[146:147], off offset:256
	s_load_dwordx2 s[26:27], s[26:27], 0x8
	s_waitcnt lgkmcnt(0)
	v_lshl_add_u64 v[148:149], s[26:27], 0, v[0:1]
	v_add_co_u32_e32 v148, vcc, s16, v148
	s_mov_b64 s[26:27], s[0:1]
	s_nop 0
	v_addc_co_u32_e32 v149, vcc, 0, v149, vcc
	global_load_dword v148, v[148:149], off
	s_load_dwordx2 s[26:27], s[26:27], 0x8
	s_waitcnt lgkmcnt(0)
; #define LDS_WAIT() asm volatile("s_waitcnt lgkmcnt(0)" ::: "memory")
; __device__ __forceinline__ const float* inp(int k) { const CAS cfptr* p = (const CAS cfptr*)__builtin_amdgcn_kernarg_segment_ptr(); asm volatile("" : "+s"(p)); return p[k]; }
; __device__ __forceinline__ void p0a(Frame& F, const Args& A) {
;     ...
;     for (int unit = F.gw; unit < 2 * 96 * 8; unit += F.NGW) {
;         const int l = unit / 768, r2 = unit % 768, cb = r2 >> 3, ks = r2 & 7, k0 = ks * 128, n = cb * 64 + f_lane;
; #pragma unroll
;         for (int r = 0; r < 9; ++r)
; #pragma unroll
;             for (int h = 0; h < 2; ++h) { const int k = k0 + h * 64 + f_lane; const float v = (r < 8) ? inp(1)[r * DM + k] : inp(3)[k]; scr[r * 128 + h * 64 + f_lane] = v * __builtin_amdgcn_rcpf(1.0f + __expf(-v)); }
;         LDS_WAIT(); asm volatile("" ::: "memory");
;         float acc[9];
;         const float bias = (ks == 0) ? inp(5)[l * MODS + n] : 0.f;
	v_lshl_add_u64 v[150:151], s[26:27], 0, v[0:1]
	v_add_co_u32_e32 v150, vcc, s16, v150
	s_mov_b64 s[26:27], s[0:1]
	s_nop 0
	v_addc_co_u32_e32 v151, vcc, 0, v151, vcc
	global_load_dword v150, v[150:151], off offset:256
	s_load_dwordx2 s[26:27], s[26:27], 0x18
	s_waitcnt lgkmcnt(0)
	global_load_dword v152, v0, s[26:27]
	s_mov_b64 s[26:27], s[0:1]
	s_waitcnt vmcnt(0)
	v_mul_f32_e32 v121, 0xbfb8aa3b, v120
	v_exp_f32_e32 v121, v121
	s_nop 0
	v_add_f32_e32 v121, 1.0, v121
	v_rcp_f32_e32 v121, v121
	s_nop 0
	v_mul_f32_e32 v120, v120, v121
	ds_write_b32 v14, v120
	v_mul_f32_e32 v123, 0xbfb8aa3b, v122
	v_exp_f32_e32 v123, v123
	s_nop 0
	v_add_f32_e32 v123, 1.0, v123
	v_rcp_f32_e32 v123, v123
	s_nop 0
	v_mul_f32_e32 v122, v122, v123
	ds_write_b32 v14, v122 offset:256
	v_mul_f32_e32 v125, 0xbfb8aa3b, v124
	v_exp_f32_e32 v125, v125
	s_nop 0
	v_add_f32_e32 v125, 1.0, v125
	v_rcp_f32_e32 v125, v125
	s_nop 0
	v_mul_f32_e32 v124, v124, v125
	ds_write_b32 v14, v124 offset:512
	v_mul_f32_e32 v127, 0xbfb8aa3b, v126
	v_exp_f32_e32 v127, v127
	s_nop 0
	v_add_f32_e32 v127, 1.0, v127
	v_rcp_f32_e32 v127, v127
	s_nop 0
	v_mul_f32_e32 v126, v126, v127
	ds_write_b32 v14, v126 offset:768
	v_mul_f32_e32 v129, 0xbfb8aa3b, v128
	v_exp_f32_e32 v129, v129
	s_nop 0
	v_add_f32_e32 v129, 1.0, v129
	v_rcp_f32_e32 v129, v129
	s_nop 0
	v_mul_f32_e32 v128, v128, v129
	ds_write_b32 v14, v128 offset:1024
	v_mul_f32_e32 v131, 0xbfb8aa3b, v130
	v_exp_f32_e32 v131, v131
	s_nop 0
	v_add_f32_e32 v131, 1.0, v131
	v_rcp_f32_e32 v131, v131
	s_nop 0
	v_mul_f32_e32 v130, v130, v131
	ds_write_b32 v14, v130 offset:1280
	v_mul_f32_e32 v133, 0xbfb8aa3b, v132
	v_exp_f32_e32 v133, v133
	s_nop 0
	v_add_f32_e32 v133, 1.0, v133
	v_rcp_f32_e32 v133, v133
	s_nop 0
	v_mul_f32_e32 v132, v132, v133
	ds_write_b32 v14, v132 offset:1536
	v_mul_f32_e32 v135, 0xbfb8aa3b, v134
	v_exp_f32_e32 v135, v135
	s_nop 0
	v_add_f32_e32 v135, 1.0, v135
	v_rcp_f32_e32 v135, v135
	s_nop 0
	v_mul_f32_e32 v134, v134, v135
	ds_write_b32 v14, v134 offset:1792
	v_mul_f32_e32 v137, 0xbfb8aa3b, v136
	v_exp_f32_e32 v137, v137
	s_nop 0
	v_add_f32_e32 v137, 1.0, v137
	v_rcp_f32_e32 v137, v137
	s_nop 0
	v_mul_f32_e32 v136, v136, v137
	ds_write_b32 v14, v136 offset:2048
	v_mul_f32_e32 v139, 0xbfb8aa3b, v138
	v_exp_f32_e32 v139, v139
	s_nop 0
	v_add_f32_e32 v139, 1.0, v139
	v_rcp_f32_e32 v139, v139
	s_nop 0
	v_mul_f32_e32 v138, v138, v139
	ds_write_b32 v14, v138 offset:2304
	v_mul_f32_e32 v141, 0xbfb8aa3b, v140
	v_exp_f32_e32 v141, v141
	s_nop 0
	v_add_f32_e32 v141, 1.0, v141
	v_rcp_f32_e32 v141, v141
	s_nop 0
	v_mul_f32_e32 v140, v140, v141
	ds_write_b32 v14, v140 offset:2560
	v_mul_f32_e32 v143, 0xbfb8aa3b, v142
	v_exp_f32_e32 v143, v143
	s_nop 0
	v_add_f32_e32 v143, 1.0, v143
	v_rcp_f32_e32 v143, v143
	s_nop 0
	v_mul_f32_e32 v142, v142, v143
	ds_write_b32 v14, v142 offset:2816
	v_mul_f32_e32 v145, 0xbfb8aa3b, v144
	v_exp_f32_e32 v145, v145
	s_nop 0
	v_add_f32_e32 v145, 1.0, v145
	v_rcp_f32_e32 v145, v145
	s_nop 0
	v_mul_f32_e32 v144, v144, v145
	ds_write_b32 v14, v144 offset:3072
	v_mul_f32_e32 v147, 0xbfb8aa3b, v146
	v_exp_f32_e32 v147, v147
	s_nop 0
	v_add_f32_e32 v147, 1.0, v147
	v_rcp_f32_e32 v147, v147
	s_nop 0
	v_mul_f32_e32 v146, v146, v147
	ds_write_b32 v14, v146 offset:3328
	v_mul_f32_e32 v149, 0xbfb8aa3b, v148
	v_exp_f32_e32 v149, v149
	s_nop 0
	v_add_f32_e32 v149, 1.0, v149
	v_rcp_f32_e32 v149, v149
	s_nop 0
	v_mul_f32_e32 v148, v148, v149
	ds_write_b32 v14, v148 offset:3584
	v_mul_f32_e32 v151, 0xbfb8aa3b, v150
	v_exp_f32_e32 v151, v151
	s_nop 0
	v_add_f32_e32 v151, 1.0, v151
	v_rcp_f32_e32 v151, v151
	s_nop 0
	v_mul_f32_e32 v150, v150, v151
	ds_write_b32 v14, v150 offset:3840
	v_mul_f32_e32 v153, 0xbfb8aa3b, v152
	v_exp_f32_e32 v153, v153
	s_nop 0
	v_add_f32_e32 v153, 1.0, v153
	v_rcp_f32_e32 v153, v153
	s_nop 0
	v_mul_f32_e32 v152, v152, v153
	ds_write_b32 v14, v152 offset:4096
	s_load_dwordx2 s[26:27], s[26:27], 0x18
	s_waitcnt lgkmcnt(0)
	global_load_dword v0, v0, s[26:27] offset:256
	s_waitcnt vmcnt(0)
	v_mul_f32_e32 v2, 0xbfb8aa3b, v0
	v_exp_f32_e32 v2, v2
	s_nop 0
	v_add_f32_e32 v2, 1.0, v2
	v_rcp_f32_e32 v2, v2
	s_nop 0
	v_mul_f32_e32 v0, v0, v2
	ds_write_b32 v14, v0 offset:4352
	s_waitcnt lgkmcnt(0)
	v_or_b32_e32 v2, s9, v48
	s_cbranch_scc1 .LBB0_125
	s_mov_b64 s[26:27], s[0:1]
	s_load_dwordx2 s[26:27], s[26:27], 0x28
	s_mul_i32 s9, s24, 0x1800
	v_add_u32_e32 v4, s9, v2
	v_ashrrev_i32_e32 v5, 31, v4
	s_waitcnt lgkmcnt(0)
	v_lshl_add_u64 v[4:5], v[4:5], 2, s[26:27]
	global_load_dword v6, v[4:5], off
